# P1 epilogue: ds_bpermute lane transpose so consecutive lanes store consecutive 16B chunks (on top of permlane merge)
# speedup vs baseline: 1.0213x; 1.0071x over previous
; #define PG8_STAGE(bufoff, gbase, voff) do { _Pragma("unroll") for (int _i = 0; _i < 2; ++_i) \
;         __builtin_amdgcn_global_load_lds((const unsigned*)((const char*)(gbase) + (voff)[_i]), (LAS unsigned*)(lds + (bufoff) + ldsw + _i * 8192), 16, 0, 0); } while (0)
; #define PG8_WAIT_V(n) asm volatile("s_waitcnt vmcnt(" #n ")" ::: "memory")
; #define PG8_BAR __builtin_amdgcn_s_barrier()
; DI u32x4 pack8(const f32x4 v0, const f32x4 v1) { u32x4 w; w.x = pk2(v0[0], v0[1]); w.y = pk2(v0[2], v0[3]); w.z = pk2(v1[0], v1[1]); w.w = pk2(v1[2], v1[3]); return w; }
; template <class Epi, bool ALIGN_EPI>
; DI void gemm_phase(const int wv, LAS unsigned char* lds, const GemmD g, const Sched& S, const Epi& E) {
;     ...
;     const char* cA = g.a(cur); const char* cB = g.b(cur);
;     PG8_STAGE(PG8_SB(0, 0), cB, voffB); PG8_STAGE(PG8_SB(0, 1), cB + hstepB, voffB); PG8_STAGE(PG8_SA(0, 0), cA, voffA); PG8_STAGE(PG8_SA(0, 1), cA + hstepA, voffA);
;     if (wr == 1) PG8_BAR;
;     PG8_WAIT_V(2); PG8_BAR;
;     PG8_STAGE(PG8_SB(1, 0), cB + kstepB, voffB); PG8_STAGE(PG8_SA(1, 0), cA + kstepA, voffA); PG8_STAGE(PG8_SB(1, 1), cB + hstepB + kstepB, voffB);
;     PG8_WAIT_V(6); PG8_BAR;
;     DI void operator()(const f32x4 (&acc)[2][2][4][2], const Unit& u, int wr, int wc, int fr, int fq) const {
;     ...
;             const int row = u.pm * 256 + ai * 128 + wr * 64 + m * 16 + fr, cl = bj * 128 + wc * 32 + 8 * fq;
;             if (cl < nc) __builtin_nontemporal_store(pack8(acc[ai][bj][m][0] * qs, acc[ai][bj][m][1] * qs), (u32x4*)(base + (size_t)row * ld + c0 + cl));
.LBB0_238:
	s_load_dwordx4 s[16:19], s[94:95], 0xd0
	s_waitcnt vmcnt(2)
	s_barrier
	v_mov_b32_e32 v141, v137
	v_mov_b32_e32 v143, v137
	s_waitcnt lgkmcnt(0)
	s_add_u32 s14, s18, 0x24000000
	s_addc_u32 s15, s19, 0
	s_add_u32 s16, s16, 0x8000000
	s_mov_b64 s[18:19], 0x80
	s_addc_u32 s17, s17, 0
	v_lshl_add_u64 v[4:5], v[4:5], 0, s[18:19]
	s_add_i32 m0, s0, 0x18000
	v_lshl_add_u64 v[2:3], v[2:3], 0, s[18:19]
	global_load_lds_dwordx4 v[4:5], off
	s_add_i32 m0, s0, 0x1a000
	s_add_i32 s30, s0, 0x8000
	s_add_i32 s31, s0, 0xa000
	global_load_lds_dwordx4 v[2:3], off
	v_lshl_add_u64 v[0:1], v[0:1], 0, s[18:19]
	s_mov_b32 m0, s30
	s_add_u32 s6, s60, 0x40080
	global_load_lds_dwordx4 v[0:1], off
	v_lshl_add_u64 v[0:1], v[6:7], 0, s[18:19]
	s_mov_b32 m0, s31
	s_addc_u32 s7, s61, 0
	global_load_lds_dwordx4 v[0:1], off
	v_lshl_add_u64 v[0:1], s[6:7], 0, v[130:131]
	s_add_i32 m0, s0, 0x1c000
	s_add_i32 s34, 0, 0x10000
	global_load_lds_dwordx4 v[0:1], off
	v_lshl_add_u64 v[0:1], s[6:7], 0, v[134:135]
	s_add_i32 m0, s0, 0x1e000
	v_readlane_b32 s6, v254, 8
	global_load_lds_dwordx4 v[0:1], off
	v_and_b32_e32 v0, 15, v8
	v_lshrrev_b32_e32 v1, 1, v8
	v_or_b32_e32 v139, s6, v0
	v_and_b32_e32 v1, 24, v1
	v_lshlrev_b32_e32 v2, 6, v139
	v_lshlrev_b32_e32 v3, 1, v1
	s_movk_i32 s6, 0x3c0
	v_lshlrev_b32_e32 v4, 2, v139
	v_and_or_b32 v2, v2, s6, v3
	v_and_b32_e32 v4, 32, v4
	v_readlane_b32 s6, v254, 9
	v_lshl_or_b32 v0, v0, 6, v3
	v_lshlrev_b32_e32 v3, 2, v8
	v_bitop3_b32 v2, v2, s6, v4 bitop3:0xde
	v_and_b32_e32 v3, 32, v3
	v_readlane_b32 s6, v254, 11
	s_waitcnt vmcnt(6)
	s_add_i32 s35, 0, 0x14000
	v_mov_b64_e32 v[144:145], 0x1900
	v_bitop3_b32 v152, v0, s6, v3 bitop3:0xde
	v_lshlrev_b32_e32 v0, 14, v9
	v_readlane_b32 s6, v254, 10
	v_and_b32_e32 v0, 0xffff8000, v0
	v_lshl_add_u32 v0, v10, 11, v0
	v_or_b32_e32 v138, s6, v1
	v_and_b32_e32 v1, 1, v9
	v_lshl_or_b32 v0, v1, 6, v0
	v_lshl_add_u32 v140, v11, 1, v0
	v_lshlrev_b32_e32 v0, 14, v12
	v_and_b32_e32 v0, 0xffff8000, v0
	v_lshl_add_u32 v0, v13, 11, v0
	v_and_b32_e32 v1, 1, v12
	v_lshl_or_b32 v0, v1, 6, v0
	v_or_b32_e32 v153, 0x80, v138
	v_mbcnt_lo_u32_b32 v229, -1, 0
	v_mbcnt_hi_u32_b32 v229, -1, v229
	v_lshrrev_b32_e32 v228, 2, v229
	v_and_b32_e32 v229, 3, v229
	v_and_b32_e32 v139, -16, v139
	v_or_b32_e32 v139, v139, v228
	v_and_b32_e32 v138, 0xffffffe7, v138
	v_lshl_or_b32 v138, v229, 3, v138
	v_or_b32_e32 v153, 0x80, v138
	v_lshl_add_u32 v228, v229, 4, v228
	v_lshlrev_b32_e32 v228, 2, v228
	v_lshl_add_u32 v142, v14, 1, v0
	v_mov_b64_e32 v[146:147], 0x18ff
	s_movk_i32 s33, 0x321
	v_add_u32_e32 v154, s34, v152
	v_add_u32_e32 v155, s35, v152
	v_add_u32_e32 v156, 0, v2
	v_mov_b32_e32 v157, 0x3e38aa3b
	s_mov_b32 s36, 0
	s_barrier
	s_branch .LBB0_241

; #define EPI_LOOP for (int ai = 0; ai < 2; ++ai) _Pragma("unroll") for (int m = 0; m < 4; ++m) _Pragma("unroll") for (int bj = 0; bj < 2; ++bj)
; DI u32x4 pack8(const f32x4 v0, const f32x4 v1) { u32x4 w; w.x = pk2(v0[0], v0[1]); w.y = pk2(v0[2], v0[3]); w.z = pk2(v1[0], v1[1]); w.w = pk2(v1[2], v1[3]); return w; }
;     DI void operator()(const f32x4 (&acc)[2][2][4][2], const Unit& u, int wr, int wc, int fr, int fq) const {
;     ...
;         const float qs = (pn >= 8 && pn < 12) ? 0.125f * LOG2E : 1.f;
; #pragma unroll
;         EPI_LOOP {
;             const int row = u.pm * 256 + ai * 128 + wr * 64 + m * 16 + fr, cl = bj * 128 + wc * 32 + 8 * fq;
;             if (cl < nc) __builtin_nontemporal_store(pack8(acc[ai][bj][m][0] * qs, acc[ai][bj][m][1] * qs), (u32x4*)(base + (size_t)row * ld + c0 + cl));
;         }
.LBB0_260:
	s_and_b32 s9, s56, -4
	s_cmp_eq_u32 s9, 8
	s_cselect_b64 vcc, -1, 0
	v_lshl_add_u32 v158, s8, 8, v139
	s_lshl_b64 s[8:9], s[10:11], 1
	s_add_u32 s56, s60, s8
	v_ashrrev_i32_e32 v136, 31, v158
	s_addc_u32 s57, s61, s9
	v_mul_lo_u32 v159, s58, v136
	v_mul_lo_u32 v136, s59, v158
	v_mad_u64_u32 v[150:151], s[8:9], s58, v158, 0
	v_cndmask_b32_e32 v148, 1.0, v157, vcc
	v_add3_u32 v151, v151, v159, v136
	v_mov_b32_e32 v149, v148
	v_lshl_add_u64 v[150:151], v[150:151], 1, s[56:57]
	v_cmp_gt_u32_e32 vcc, s21, v138
	v_lshlrev_b32_e32 v136, 1, v138
	s_and_saveexec_b64 s[8:9], vcc
	s_cbranch_execz .LBB0_262
	v_mov_b32_e32 v160, v148
	v_mov_b32_e32 v161, v148
	v_pk_mul_f32 v[126:127], v[160:161], v[126:127]
	v_pk_mul_f32 v[124:125], v[148:149], v[124:125]
	v_pk_mul_f32 v[160:161], v[160:161], v[122:123]
	v_pk_mul_f32 v[122:123], v[148:149], v[120:121]
	v_cvt_pk_bf16_f32 v120, v124, v125
	v_cvt_pk_bf16_f32 v121, v126, v127
	v_cvt_pk_bf16_f32 v122, v122, v123
	v_cvt_pk_bf16_f32 v123, v160, v161
	v_lshl_add_u64 v[124:125], v[150:151], 0, v[136:137]
	ds_bpermute_b32 v120, v228, v120
	ds_bpermute_b32 v121, v228, v121
	ds_bpermute_b32 v122, v228, v122
	ds_bpermute_b32 v123, v228, v123
	s_waitcnt lgkmcnt(0)
	global_store_dwordx4 v[124:125], v[120:123], off nt
.LBB0_262:
	s_or_b64 exec, exec, s[8:9]
	v_cmp_gt_u32_e64 s[8:9], s21, v153
	s_and_saveexec_b64 s[60:61], s[8:9]
	s_cbranch_execz .LBB0_264
	v_mov_b32_e32 v120, v148
	v_mov_b32_e32 v121, v148
	v_pk_mul_f32 v[118:119], v[120:121], v[118:119]
	v_pk_mul_f32 v[116:117], v[148:149], v[116:117]
	v_pk_mul_f32 v[120:121], v[120:121], v[114:115]
	v_pk_mul_f32 v[114:115], v[148:149], v[112:113]
	v_cvt_pk_bf16_f32 v112, v116, v117
	v_cvt_pk_bf16_f32 v113, v118, v119
	v_cvt_pk_bf16_f32 v114, v114, v115
	v_cvt_pk_bf16_f32 v115, v120, v121
	v_lshl_add_u64 v[116:117], v[150:151], 0, v[136:137]
	ds_bpermute_b32 v112, v228, v112
	ds_bpermute_b32 v113, v228, v113
	ds_bpermute_b32 v114, v228, v114
	ds_bpermute_b32 v115, v228, v115
	s_waitcnt lgkmcnt(0)
	global_store_dwordx4 v[116:117], v[112:115], off offset:256 nt
.LBB0_264:
	s_or_b64 exec, exec, s[60:61]
	s_nop 0
	v_or_b32_e32 v112, 16, v158
	v_mul_lo_u32 v114, s59, v112
	v_mad_u64_u32 v[112:113], s[38:39], s58, v112, 0
	v_add3_u32 v113, v113, v159, v114
	v_lshl_add_u64 v[112:113], v[112:113], 1, s[56:57]
	s_and_saveexec_b64 s[60:61], vcc
	s_cbranch_execz .LBB0_266
	v_mov_b32_e32 v114, v148
	v_mov_b32_e32 v115, v148
	v_pk_mul_f32 v[110:111], v[114:115], v[110:111]
	v_pk_mul_f32 v[108:109], v[148:149], v[108:109]
	v_pk_mul_f32 v[114:115], v[114:115], v[106:107]
	v_pk_mul_f32 v[106:107], v[148:149], v[104:105]
	v_cvt_pk_bf16_f32 v104, v108, v109
	v_cvt_pk_bf16_f32 v105, v110, v111
	v_cvt_pk_bf16_f32 v106, v106, v107
	v_cvt_pk_bf16_f32 v107, v114, v115
	v_lshl_add_u64 v[108:109], v[112:113], 0, v[136:137]
	ds_bpermute_b32 v104, v228, v104
	ds_bpermute_b32 v105, v228, v105
	ds_bpermute_b32 v106, v228, v106
	ds_bpermute_b32 v107, v228, v107
	s_waitcnt lgkmcnt(0)
	global_store_dwordx4 v[108:109], v[104:107], off nt
.LBB0_266:
	s_or_b64 exec, exec, s[60:61]
	s_and_saveexec_b64 s[60:61], s[8:9]
	s_cbranch_execz .LBB0_268
	v_mov_b32_e32 v104, v148
	v_mov_b32_e32 v105, v148
	v_pk_mul_f32 v[102:103], v[104:105], v[102:103]
	v_pk_mul_f32 v[100:101], v[148:149], v[100:101]
	v_pk_mul_f32 v[104:105], v[104:105], v[98:99]
	v_pk_mul_f32 v[98:99], v[148:149], v[96:97]
	v_cvt_pk_bf16_f32 v96, v100, v101
	v_cvt_pk_bf16_f32 v97, v102, v103
	v_cvt_pk_bf16_f32 v98, v98, v99
	v_cvt_pk_bf16_f32 v99, v104, v105
	v_lshl_add_u64 v[100:101], v[112:113], 0, v[136:137]
	ds_bpermute_b32 v96, v228, v96
	ds_bpermute_b32 v97, v228, v97
	ds_bpermute_b32 v98, v228, v98
	ds_bpermute_b32 v99, v228, v99
	s_waitcnt lgkmcnt(0)
	global_store_dwordx4 v[100:101], v[96:99], off offset:256 nt
.LBB0_268:
	s_or_b64 exec, exec, s[60:61]
	s_nop 0
	v_or_b32_e32 v96, 32, v158
	v_mul_lo_u32 v98, s59, v96
	v_mad_u64_u32 v[96:97], s[38:39], s58, v96, 0
	v_add3_u32 v97, v97, v159, v98
	v_lshl_add_u64 v[96:97], v[96:97], 1, s[56:57]
	s_and_saveexec_b64 s[60:61], vcc
	s_cbranch_execz .LBB0_270
	v_mov_b32_e32 v98, v148
	v_mov_b32_e32 v99, v148
	v_pk_mul_f32 v[94:95], v[98:99], v[94:95]
	v_pk_mul_f32 v[92:93], v[148:149], v[92:93]
	v_pk_mul_f32 v[98:99], v[98:99], v[90:91]
	v_pk_mul_f32 v[90:91], v[148:149], v[88:89]
	v_cvt_pk_bf16_f32 v88, v92, v93
	v_cvt_pk_bf16_f32 v89, v94, v95
	v_cvt_pk_bf16_f32 v90, v90, v91
	v_cvt_pk_bf16_f32 v91, v98, v99
	v_lshl_add_u64 v[92:93], v[96:97], 0, v[136:137]
	ds_bpermute_b32 v88, v228, v88
	ds_bpermute_b32 v89, v228, v89
	ds_bpermute_b32 v90, v228, v90
	ds_bpermute_b32 v91, v228, v91
	s_waitcnt lgkmcnt(0)
	global_store_dwordx4 v[92:93], v[88:91], off nt
.LBB0_270:
	s_or_b64 exec, exec, s[60:61]
	s_and_saveexec_b64 s[60:61], s[8:9]
	s_cbranch_execz .LBB0_272
	v_mov_b32_e32 v88, v148
	v_mov_b32_e32 v89, v148
	v_pk_mul_f32 v[86:87], v[88:89], v[86:87]
	v_pk_mul_f32 v[84:85], v[148:149], v[84:85]
	v_pk_mul_f32 v[88:89], v[88:89], v[82:83]
	v_pk_mul_f32 v[82:83], v[148:149], v[80:81]
	v_cvt_pk_bf16_f32 v80, v84, v85
	v_cvt_pk_bf16_f32 v81, v86, v87
	v_cvt_pk_bf16_f32 v82, v82, v83
	v_cvt_pk_bf16_f32 v83, v88, v89
	v_lshl_add_u64 v[84:85], v[96:97], 0, v[136:137]
	ds_bpermute_b32 v80, v228, v80
	ds_bpermute_b32 v81, v228, v81
	ds_bpermute_b32 v82, v228, v82
	ds_bpermute_b32 v83, v228, v83
	s_waitcnt lgkmcnt(0)
	global_store_dwordx4 v[84:85], v[80:83], off offset:256 nt
; #define EPI_LOOP for (int ai = 0; ai < 2; ++ai) _Pragma("unroll") for (int m = 0; m < 4; ++m) _Pragma("unroll") for (int bj = 0; bj < 2; ++bj)
; DI u32x4 pack8(const f32x4 v0, const f32x4 v1) { u32x4 w; w.x = pk2(v0[0], v0[1]); w.y = pk2(v0[2], v0[3]); w.z = pk2(v1[0], v1[1]); w.w = pk2(v1[2], v1[3]); return w; }
;     DI void operator()(const f32x4 (&acc)[2][2][4][2], const Unit& u, int wr, int wc, int fr, int fq) const {
;     ...
;         const float qs = (pn >= 8 && pn < 12) ? 0.125f * LOG2E : 1.f;
; #pragma unroll
;         EPI_LOOP {
;             const int row = u.pm * 256 + ai * 128 + wr * 64 + m * 16 + fr, cl = bj * 128 + wc * 32 + 8 * fq;
;             if (cl < nc) __builtin_nontemporal_store(pack8(acc[ai][bj][m][0] * qs, acc[ai][bj][m][1] * qs), (u32x4*)(base + (size_t)row * ld + c0 + cl));
;         }
.LBB0_272:
	s_or_b64 exec, exec, s[60:61]
	s_nop 0
	v_or_b32_e32 v80, 48, v158
	v_mul_lo_u32 v82, s59, v80
	v_mad_u64_u32 v[80:81], s[38:39], s58, v80, 0
	v_add3_u32 v81, v81, v159, v82
	v_lshl_add_u64 v[80:81], v[80:81], 1, s[56:57]
	s_and_saveexec_b64 s[60:61], vcc
	s_cbranch_execz .LBB0_274
	v_mov_b32_e32 v82, v148
	v_mov_b32_e32 v83, v148
	v_pk_mul_f32 v[78:79], v[82:83], v[78:79]
	v_pk_mul_f32 v[76:77], v[148:149], v[76:77]
	v_pk_mul_f32 v[82:83], v[82:83], v[74:75]
	v_pk_mul_f32 v[74:75], v[148:149], v[72:73]
	v_cvt_pk_bf16_f32 v72, v76, v77
	v_cvt_pk_bf16_f32 v73, v78, v79
	v_cvt_pk_bf16_f32 v74, v74, v75
	v_cvt_pk_bf16_f32 v75, v82, v83
	v_lshl_add_u64 v[76:77], v[80:81], 0, v[136:137]
	ds_bpermute_b32 v72, v228, v72
	ds_bpermute_b32 v73, v228, v73
	ds_bpermute_b32 v74, v228, v74
	ds_bpermute_b32 v75, v228, v75
	s_waitcnt lgkmcnt(0)
	global_store_dwordx4 v[76:77], v[72:75], off nt
.LBB0_274:
	s_or_b64 exec, exec, s[60:61]
	s_and_saveexec_b64 s[60:61], s[8:9]
	s_cbranch_execz .LBB0_276
	v_mov_b32_e32 v72, v148
	v_mov_b32_e32 v73, v148
	v_pk_mul_f32 v[70:71], v[72:73], v[70:71]
	v_pk_mul_f32 v[68:69], v[148:149], v[68:69]
	v_pk_mul_f32 v[72:73], v[72:73], v[66:67]
	v_pk_mul_f32 v[66:67], v[148:149], v[64:65]
	v_cvt_pk_bf16_f32 v64, v68, v69
	v_cvt_pk_bf16_f32 v65, v70, v71
	v_cvt_pk_bf16_f32 v66, v66, v67
	v_cvt_pk_bf16_f32 v67, v72, v73
	v_lshl_add_u64 v[68:69], v[80:81], 0, v[136:137]
	ds_bpermute_b32 v64, v228, v64
	ds_bpermute_b32 v65, v228, v65
	ds_bpermute_b32 v66, v228, v66
	ds_bpermute_b32 v67, v228, v67
	s_waitcnt lgkmcnt(0)
	global_store_dwordx4 v[68:69], v[64:67], off offset:256 nt
.LBB0_276:
	s_or_b64 exec, exec, s[60:61]
	s_nop 0
	v_add_u32_e32 v64, 0x80, v158
	v_ashrrev_i32_e32 v65, 31, v64
	v_mul_lo_u32 v66, s58, v65
	v_mul_lo_u32 v67, s59, v64
	v_mad_u64_u32 v[64:65], s[38:39], s58, v64, 0
	v_add3_u32 v65, v65, v66, v67
	v_lshl_add_u64 v[64:65], v[64:65], 1, s[56:57]
	s_and_saveexec_b64 s[60:61], vcc
	s_cbranch_execz .LBB0_278
	v_mov_b32_e32 v66, v148
	v_mov_b32_e32 v67, v148
	v_pk_mul_f32 v[62:63], v[66:67], v[62:63]
	v_pk_mul_f32 v[60:61], v[148:149], v[60:61]
	v_pk_mul_f32 v[66:67], v[66:67], v[58:59]
	v_pk_mul_f32 v[58:59], v[148:149], v[56:57]
	v_cvt_pk_bf16_f32 v56, v60, v61
	v_cvt_pk_bf16_f32 v57, v62, v63
	v_cvt_pk_bf16_f32 v58, v58, v59
	v_cvt_pk_bf16_f32 v59, v66, v67
	v_lshl_add_u64 v[60:61], v[64:65], 0, v[136:137]
	ds_bpermute_b32 v56, v228, v56
	ds_bpermute_b32 v57, v228, v57
	ds_bpermute_b32 v58, v228, v58
	ds_bpermute_b32 v59, v228, v59
	s_waitcnt lgkmcnt(0)
	global_store_dwordx4 v[60:61], v[56:59], off nt
.LBB0_278:
	s_or_b64 exec, exec, s[60:61]
	s_and_saveexec_b64 s[60:61], s[8:9]
	s_cbranch_execz .LBB0_280
	v_mov_b32_e32 v56, v148
	v_mov_b32_e32 v57, v148
	v_pk_mul_f32 v[54:55], v[56:57], v[54:55]
	v_pk_mul_f32 v[52:53], v[148:149], v[52:53]
	v_pk_mul_f32 v[56:57], v[56:57], v[50:51]
	v_pk_mul_f32 v[50:51], v[148:149], v[48:49]
	v_cvt_pk_bf16_f32 v48, v52, v53
	v_cvt_pk_bf16_f32 v49, v54, v55
	v_cvt_pk_bf16_f32 v50, v50, v51
	v_cvt_pk_bf16_f32 v51, v56, v57
	v_lshl_add_u64 v[52:53], v[64:65], 0, v[136:137]
	ds_bpermute_b32 v48, v228, v48
	ds_bpermute_b32 v49, v228, v49
	ds_bpermute_b32 v50, v228, v50
	ds_bpermute_b32 v51, v228, v51
	s_waitcnt lgkmcnt(0)
	global_store_dwordx4 v[52:53], v[48:51], off offset:256 nt
.LBB0_280:
	s_or_b64 exec, exec, s[60:61]
	s_nop 0
	v_add_u32_e32 v48, 0x90, v158
	v_ashrrev_i32_e32 v49, 31, v48
	v_mul_lo_u32 v50, s58, v49
	v_mul_lo_u32 v51, s59, v48
	v_mad_u64_u32 v[48:49], s[38:39], s58, v48, 0
	v_add3_u32 v49, v49, v50, v51
	v_lshl_add_u64 v[48:49], v[48:49], 1, s[56:57]
	s_and_saveexec_b64 s[60:61], vcc
	s_cbranch_execz .LBB0_282
	v_mov_b32_e32 v50, v148
	v_mov_b32_e32 v51, v148
	v_pk_mul_f32 v[46:47], v[50:51], v[46:47]
	v_pk_mul_f32 v[44:45], v[148:149], v[44:45]
	v_pk_mul_f32 v[50:51], v[50:51], v[42:43]
	v_pk_mul_f32 v[42:43], v[148:149], v[40:41]
	v_cvt_pk_bf16_f32 v40, v44, v45
	v_cvt_pk_bf16_f32 v41, v46, v47
	v_cvt_pk_bf16_f32 v42, v42, v43
	v_cvt_pk_bf16_f32 v43, v50, v51
	v_lshl_add_u64 v[44:45], v[48:49], 0, v[136:137]
	ds_bpermute_b32 v40, v228, v40
	ds_bpermute_b32 v41, v228, v41
	ds_bpermute_b32 v42, v228, v42
	ds_bpermute_b32 v43, v228, v43
	s_waitcnt lgkmcnt(0)
	global_store_dwordx4 v[44:45], v[40:43], off nt
.LBB0_282:
	s_or_b64 exec, exec, s[60:61]
	s_and_saveexec_b64 s[60:61], s[8:9]
	s_cbranch_execz .LBB0_284
	v_mov_b32_e32 v40, v148
	v_mov_b32_e32 v41, v148
	v_pk_mul_f32 v[38:39], v[40:41], v[38:39]
	v_pk_mul_f32 v[36:37], v[148:149], v[36:37]
	v_pk_mul_f32 v[40:41], v[40:41], v[34:35]
	v_pk_mul_f32 v[34:35], v[148:149], v[32:33]
	v_cvt_pk_bf16_f32 v32, v36, v37
	v_cvt_pk_bf16_f32 v33, v38, v39
	v_cvt_pk_bf16_f32 v34, v34, v35
	v_cvt_pk_bf16_f32 v35, v40, v41
	v_lshl_add_u64 v[36:37], v[48:49], 0, v[136:137]
	ds_bpermute_b32 v32, v228, v32
	ds_bpermute_b32 v33, v228, v33
	ds_bpermute_b32 v34, v228, v34
	ds_bpermute_b32 v35, v228, v35
	s_waitcnt lgkmcnt(0)
	global_store_dwordx4 v[36:37], v[32:35], off offset:256 nt
.LBB0_284:
	s_or_b64 exec, exec, s[60:61]
	s_nop 0
	v_add_u32_e32 v32, 0xa0, v158
	v_ashrrev_i32_e32 v33, 31, v32
	v_mul_lo_u32 v34, s58, v33
	v_mul_lo_u32 v35, s59, v32
	v_mad_u64_u32 v[32:33], s[38:39], s58, v32, 0
	v_add3_u32 v33, v33, v34, v35
	v_lshl_add_u64 v[32:33], v[32:33], 1, s[56:57]
	s_and_saveexec_b64 s[60:61], vcc
	s_cbranch_execz .LBB0_286
	v_mov_b32_e32 v34, v148
	v_mov_b32_e32 v35, v148
	v_pk_mul_f32 v[30:31], v[34:35], v[30:31]
	v_pk_mul_f32 v[28:29], v[148:149], v[28:29]
	v_pk_mul_f32 v[34:35], v[34:35], v[26:27]
	v_pk_mul_f32 v[26:27], v[148:149], v[24:25]
	v_cvt_pk_bf16_f32 v24, v28, v29
	v_cvt_pk_bf16_f32 v25, v30, v31
	v_cvt_pk_bf16_f32 v26, v26, v27
	v_cvt_pk_bf16_f32 v27, v34, v35
	v_lshl_add_u64 v[28:29], v[32:33], 0, v[136:137]
	ds_bpermute_b32 v24, v228, v24
	ds_bpermute_b32 v25, v228, v25
	ds_bpermute_b32 v26, v228, v26
	ds_bpermute_b32 v27, v228, v27
	s_waitcnt lgkmcnt(0)
	global_store_dwordx4 v[28:29], v[24:27], off nt
.LBB0_286:
	s_or_b64 exec, exec, s[60:61]
	s_and_saveexec_b64 s[60:61], s[8:9]
	s_cbranch_execz .LBB0_288
	v_mov_b32_e32 v24, v148
	v_mov_b32_e32 v25, v148
	v_pk_mul_f32 v[22:23], v[24:25], v[22:23]
	v_pk_mul_f32 v[20:21], v[148:149], v[20:21]
	v_pk_mul_f32 v[24:25], v[24:25], v[18:19]
	v_pk_mul_f32 v[18:19], v[148:149], v[16:17]
	v_cvt_pk_bf16_f32 v16, v20, v21
	v_cvt_pk_bf16_f32 v17, v22, v23
	v_cvt_pk_bf16_f32 v18, v18, v19
	v_cvt_pk_bf16_f32 v19, v24, v25
	v_lshl_add_u64 v[20:21], v[32:33], 0, v[136:137]
	ds_bpermute_b32 v16, v228, v16
	ds_bpermute_b32 v17, v228, v17
	ds_bpermute_b32 v18, v228, v18
	ds_bpermute_b32 v19, v228, v19
	s_waitcnt lgkmcnt(0)
	global_store_dwordx4 v[20:21], v[16:19], off offset:256 nt

; #define EPI_LOOP for (int ai = 0; ai < 2; ++ai) _Pragma("unroll") for (int m = 0; m < 4; ++m) _Pragma("unroll") for (int bj = 0; bj < 2; ++bj)
; DI u32x4 pack8(const f32x4 v0, const f32x4 v1) { u32x4 w; w.x = pk2(v0[0], v0[1]); w.y = pk2(v0[2], v0[3]); w.z = pk2(v1[0], v1[1]); w.w = pk2(v1[2], v1[3]); return w; }
;     DI void operator()(const f32x4 (&acc)[2][2][4][2], const Unit& u, int wr, int wc, int fr, int fq) const {
;     ...
;         const float qs = (pn >= 8 && pn < 12) ? 0.125f * LOG2E : 1.f;
; #pragma unroll
;         EPI_LOOP {
;             const int row = u.pm * 256 + ai * 128 + wr * 64 + m * 16 + fr, cl = bj * 128 + wc * 32 + 8 * fq;
;             if (cl < nc) __builtin_nontemporal_store(pack8(acc[ai][bj][m][0] * qs, acc[ai][bj][m][1] * qs), (u32x4*)(base + (size_t)row * ld + c0 + cl));
;         }
.LBB0_291:
	v_mov_b32_e32 v18, v148
	v_mov_b32_e32 v19, v148
	v_pk_mul_f32 v[14:15], v[18:19], v[14:15]
	v_pk_mul_f32 v[12:13], v[148:149], v[12:13]
	v_pk_mul_f32 v[18:19], v[18:19], v[10:11]
	v_pk_mul_f32 v[10:11], v[148:149], v[8:9]
	v_cvt_pk_bf16_f32 v8, v12, v13
	v_cvt_pk_bf16_f32 v9, v14, v15
	v_cvt_pk_bf16_f32 v10, v10, v11
	v_cvt_pk_bf16_f32 v11, v18, v19
	v_lshl_add_u64 v[12:13], v[16:17], 0, v[136:137]
	ds_bpermute_b32 v8, v228, v8
	ds_bpermute_b32 v9, v228, v9
	ds_bpermute_b32 v10, v228, v10
	ds_bpermute_b32 v11, v228, v11
	s_waitcnt lgkmcnt(0)
	global_store_dwordx4 v[12:13], v[8:11], off nt
	s_or_b64 exec, exec, s[56:57]
	s_and_saveexec_b64 s[56:57], s[8:9]
	s_cbranch_execz .LBB0_290
.LBB0_292:
	v_mov_b32_e32 v8, v148
	v_mov_b32_e32 v9, v148
	v_pk_mul_f32 v[6:7], v[8:9], v[6:7]
	v_pk_mul_f32 v[4:5], v[148:149], v[4:5]
	v_pk_mul_f32 v[8:9], v[8:9], v[2:3]
	v_pk_mul_f32 v[2:3], v[148:149], v[0:1]
	v_cvt_pk_bf16_f32 v0, v4, v5
	v_cvt_pk_bf16_f32 v1, v6, v7
	v_cvt_pk_bf16_f32 v2, v2, v3
	v_cvt_pk_bf16_f32 v3, v8, v9
	v_lshl_add_u64 v[4:5], v[16:17], 0, v[136:137]
	ds_bpermute_b32 v0, v228, v0
	ds_bpermute_b32 v1, v228, v1
	ds_bpermute_b32 v2, v228, v2
	ds_bpermute_b32 v3, v228, v3
	s_waitcnt lgkmcnt(0)
	global_store_dwordx4 v[4:5], v[0:3], off offset:256 nt
	s_or_b64 exec, exec, s[56:57]
	s_andn2_b64 vcc, exec, s[6:7]
	s_mov_b64 s[6:7], -1
	s_cbranch_vccnz .LBB0_240
